# grid barrier: wave 0 of blocks 0-7 (one early-finishing block per XCD) issues an L2 write-back on arrival so the XCD's last arriver has less to flush
# baseline (speedup 1.0000x reference)
.LBB0_79:
	s_cbranch_execz .LBB0_133
	v_readlane_b32 s98, v248, 0
	s_cmpk_gt_u32 s98, 7
	s_cbranch_scc1 .Lef_15
	v_readfirstlane_b32 s98, v1
	s_cmpk_gt_u32 s98, 63
	s_cbranch_scc1 .Lef_15
	s_waitcnt vmcnt(0)
	buffer_wbl2 sc1
	s_waitcnt vmcnt(0)
.Lef_15:
	s_waitcnt vmcnt(0)
	s_barrier
	s_mov_b64 s[0:1], exec
	v_readlane_b32 s2, v248, 4
	v_readlane_b32 s3, v248, 5
	s_and_b64 s[2:3], s[0:1], s[2:3]
	s_mov_b64 exec, s[2:3]
	s_cbranch_execz .LBB0_132
	v_mov_b32_e32 v2, 0x12000
	s_waitcnt vmcnt(0) expcnt(0) lgkmcnt(0)
	ds_read_b32 v4, v2
	v_mov_b32_e32 v2, 0x12004
	ds_read_b32 v2, v2
	s_waitcnt lgkmcnt(1)
	v_cmp_ne_u32_e32 vcc, 0, v4
	s_cbranch_vccnz .LBB0_96
	v_readlane_b32 s2, v248, 1
	s_mul_i32 s33, s51, s2
	s_add_u32 s2, s82, 0xe968300
	s_addc_u32 s3, s83, 0
	s_add_u32 s4, s82, 0xe968500
	s_addc_u32 s5, s83, 0
	s_add_u32 s6, s82, 0xe968600
	s_addc_u32 s7, s83, 0
	s_add_u32 s8, s82, 0xe968700
	s_addc_u32 s9, s83, 0
	s_add_u32 s10, s82, 0xe968800
	s_addc_u32 s11, s83, 0
	s_add_u32 s12, s82, 0xe968900
	s_addc_u32 s13, s83, 0
	s_add_u32 s14, s82, 0xe968a00
	s_addc_u32 s15, s83, 0
	s_add_u32 s16, s82, 0xe968b00
	s_addc_u32 s17, s83, 0
	s_add_u32 s18, s82, 0xe968c00
	s_addc_u32 s19, s83, 0
	s_add_u32 s20, s82, 0xe968d00
	s_addc_u32 s21, s83, 0
	s_add_u32 s22, s82, 0xe968e00
	s_addc_u32 s23, s83, 0
	s_add_u32 s24, s82, 0xe968f00
	s_addc_u32 s25, s83, 0
	s_add_u32 s26, s82, 0xe969000
	s_addc_u32 s27, s83, 0
	s_add_u32 s28, s82, 0xe969100
	s_addc_u32 s29, s83, 0
	s_add_u32 s30, s82, 0xe969200
	s_addc_u32 s31, s83, 0
	s_add_u32 s34, s82, 0xe969300
	s_addc_u32 s35, s83, 0
	s_add_u32 s36, s82, 0xe969400
	s_mul_i32 s33, s33, s50
	s_addc_u32 s37, s83, 0
	s_mov_b32 s44, 1
	v_mov_b32_e32 v18, 0
	s_branch .LBB0_84

.Lef_13:
	s_waitcnt vmcnt(0)
	s_waitcnt vmcnt(63) expcnt(7) lgkmcnt(15)
	s_barrier
	s_mov_b64 s[0:1], exec
	v_readlane_b32 s2, v248, 4
	v_readlane_b32 s3, v248, 5
	s_and_b64 s[2:3], s[0:1], s[2:3]
	s_mov_b64 exec, s[2:3]
	s_cbranch_execz .LBB0_548
	v_mov_b32_e32 v2, 0x12000
	s_waitcnt vmcnt(0) expcnt(0) lgkmcnt(0)
	ds_read_b32 v4, v2
	v_mov_b32_e32 v2, 0x12004
	ds_read_b32 v2, v2
	s_waitcnt lgkmcnt(1)
	v_cmp_ne_u32_e32 vcc, 0, v4
	s_cbranch_vccnz .LBB0_512
	v_readlane_b32 s2, v248, 1
	s_mul_i32 s33, s51, s2
	s_add_u32 s2, s82, 0xe968300
	s_addc_u32 s3, s83, 0
	s_add_u32 s4, s82, 0xe968500
	s_addc_u32 s5, s83, 0
	s_add_u32 s6, s82, 0xe968600
	s_addc_u32 s7, s83, 0
	s_add_u32 s8, s82, 0xe968700
	s_addc_u32 s9, s83, 0
	s_add_u32 s10, s82, 0xe968800
	s_addc_u32 s11, s83, 0
	s_add_u32 s12, s82, 0xe968900
	s_addc_u32 s13, s83, 0
	s_add_u32 s14, s82, 0xe968a00
	s_addc_u32 s15, s83, 0
	s_add_u32 s16, s82, 0xe968b00
	s_addc_u32 s17, s83, 0
	s_add_u32 s18, s82, 0xe968c00
	s_addc_u32 s19, s83, 0
	s_add_u32 s20, s82, 0xe968d00
	s_addc_u32 s21, s83, 0
	s_add_u32 s22, s82, 0xe968e00
	s_addc_u32 s23, s83, 0
	s_add_u32 s24, s82, 0xe968f00
	s_addc_u32 s25, s83, 0
	s_add_u32 s26, s82, 0xe969000
	s_addc_u32 s27, s83, 0
	s_add_u32 s28, s82, 0xe969100
	s_addc_u32 s29, s83, 0
	s_add_u32 s30, s82, 0xe969200
	s_addc_u32 s31, s83, 0
	s_add_u32 s34, s82, 0xe969300
	s_addc_u32 s35, s83, 0
	s_add_u32 s36, s82, 0xe969400
	s_mul_i32 s33, s33, s50
	s_addc_u32 s37, s83, 0
	s_mov_b32 s44, 1
	v_mov_b32_e32 v18, 0
	s_branch .LBB0_500

.Lef_0:
	s_waitcnt vmcnt(0)
	s_waitcnt vmcnt(63) expcnt(7) lgkmcnt(15)
	s_barrier
	s_mov_b64 s[0:1], exec
	v_readlane_b32 s2, v248, 4
	v_readlane_b32 s3, v248, 5
	s_and_b64 s[2:3], s[0:1], s[2:3]
	s_mov_b64 exec, s[2:3]
	s_cbranch_execz .LBB0_2010
	v_mov_b32_e32 v0, 0x12000
	s_waitcnt vmcnt(0) expcnt(0) lgkmcnt(0)
	ds_read_b32 v2, v0
	v_mov_b32_e32 v0, 0x12004
	ds_read_b32 v0, v0
	s_waitcnt lgkmcnt(1)
	v_cmp_ne_u32_e32 vcc, 0, v2
	s_cbranch_vccnz .LBB0_1974
	v_readlane_b32 s2, v248, 1
	s_mul_i32 s33, s51, s2
	s_add_u32 s2, s82, 0xe968300
	s_addc_u32 s3, s83, 0
	s_add_u32 s4, s82, 0xe968500
	s_addc_u32 s5, s83, 0
	s_add_u32 s6, s82, 0xe968600
	s_addc_u32 s7, s83, 0
	s_add_u32 s8, s82, 0xe968700
	s_addc_u32 s9, s83, 0
	s_add_u32 s10, s82, 0xe968800
	s_addc_u32 s11, s83, 0
	s_add_u32 s12, s82, 0xe968900
	s_addc_u32 s13, s83, 0
	s_add_u32 s14, s82, 0xe968a00
	s_addc_u32 s15, s83, 0
	s_add_u32 s16, s82, 0xe968b00
	s_addc_u32 s17, s83, 0
	s_add_u32 s18, s82, 0xe968c00
	s_addc_u32 s19, s83, 0
	s_add_u32 s20, s82, 0xe968d00
	s_addc_u32 s21, s83, 0
	s_add_u32 s22, s82, 0xe968e00
	s_addc_u32 s23, s83, 0
	s_add_u32 s24, s82, 0xe968f00
	s_addc_u32 s25, s83, 0
	s_add_u32 s26, s82, 0xe969000
	s_addc_u32 s27, s83, 0
	s_add_u32 s28, s82, 0xe969100
	s_addc_u32 s29, s83, 0
	s_add_u32 s30, s82, 0xe969200
	s_addc_u32 s31, s83, 0
	s_add_u32 s34, s82, 0xe969300
	s_addc_u32 s35, s83, 0
	s_add_u32 s36, s82, 0xe969400
	s_mul_i32 s33, s33, s50
	s_addc_u32 s37, s83, 0
	s_mov_b32 s44, 1
	v_mov_b32_e32 v16, 0
	s_branch .LBB0_1962
